# GEMM: peeled first K iteration with SrcC=0 instead of 128 accumulator-zeroing moves per tile
# speedup vs baseline: 1.0118x; 1.0118x over previous
.LBB0_918:
	s_add_u32 s38, s18, 0x100
	s_addc_u32 s39, s19, 0
	s_add_u32 s18, s20, 0x80
	s_addc_u32 s19, s21, 0
	s_mov_b32 s20, 0
.Lgemm_k_first:
	s_add_i32 s42, s20, 2
	s_add_u32 s24, s18, 0x80
	s_addc_u32 s21, s19, 0
	s_add_i32 s43, 0, 0x10000
	v_add_u32_e32 v0, s43, v211
	s_waitcnt lgkmcnt(0)
	ds_read_b128 v[130:133], v0
	ds_read_b128 v[134:137], v0 offset:1024
	ds_read_b128 v[138:141], v0 offset:2048
	ds_read_b128 v[142:145], v0 offset:3072
	s_cmp_eq_u32 s66, s20
	s_cselect_b32 s20, s74, s24
	s_cselect_b32 s21, s75, s21
	s_cselect_b32 s25, s77, s39
	s_cselect_b32 s24, s76, s38
	v_lshl_add_u64 v[198:199], s[18:19], 0, v[184:185]
	s_add_i32 m0, s31, 0xc000
	ds_read_b128 v[146:149], v212
	ds_read_b128 v[150:153], v212 offset:1024
	ds_read_b128 v[154:157], v212 offset:2048
	ds_read_b128 v[158:161], v212 offset:3072
	ds_read_b128 v[186:189], v212 offset:4096
	ds_read_b128 v[190:193], v212 offset:5120
	ds_read_b128 v[194:197], v212 offset:6144
	ds_read_b128 v[214:217], v212 offset:7168
	global_load_lds_dwordx4 v[198:199], off
	v_lshl_add_u64 v[198:199], s[18:19], 0, v[182:183]
	s_add_i32 m0, s31, 0xe000
	s_nop 0
	global_load_lds_dwordx4 v[198:199], off
	s_waitcnt lgkmcnt(8)
	s_barrier
	s_waitcnt lgkmcnt(0)
	s_setprio 1
	s_waitcnt lgkmcnt(0)
	v_mfma_f32_16x16x32_bf16 v[126:129], v[130:133], v[146:149], 0
	v_mfma_f32_16x16x32_bf16 v[122:125], v[138:141], v[146:149], 0
	v_mfma_f32_16x16x32_bf16 v[110:113], v[130:133], v[154:157], 0
	v_mfma_f32_16x16x32_bf16 v[106:109], v[138:141], v[154:157], 0
	v_mfma_f32_16x16x32_bf16 v[94:97], v[130:133], v[186:189], 0
	v_mfma_f32_16x16x32_bf16 v[90:93], v[138:141], v[186:189], 0
	v_mfma_f32_16x16x32_bf16 v[78:81], v[130:133], v[194:197], 0
	v_mfma_f32_16x16x32_bf16 v[74:77], v[138:141], v[194:197], 0
	v_mfma_f32_16x16x32_bf16 v[126:129], v[134:137], v[150:153], v[126:129]
	v_mfma_f32_16x16x32_bf16 v[122:125], v[142:145], v[150:153], v[122:125]
	v_mfma_f32_16x16x32_bf16 v[110:113], v[134:137], v[158:161], v[110:113]
	v_mfma_f32_16x16x32_bf16 v[106:109], v[142:145], v[158:161], v[106:109]
	v_mfma_f32_16x16x32_bf16 v[94:97], v[134:137], v[190:193], v[94:97]
	v_mfma_f32_16x16x32_bf16 v[90:93], v[142:145], v[190:193], v[90:93]
	v_mfma_f32_16x16x32_bf16 v[78:81], v[134:137], v[214:217], v[78:81]
	v_mfma_f32_16x16x32_bf16 v[74:77], v[142:145], v[214:217], v[74:77]
	s_setprio 0
	s_barrier
	s_add_i32 s44, 0, 0x14000
	s_add_i32 s43, s43, s30
	v_add_u32_e32 v0, s44, v211
	v_lshl_add_u64 v[198:199], s[24:25], 0, v[170:171]
	s_mov_b32 m0, s43
	ds_read_b128 v[232:235], v0
	ds_read_b128 v[236:239], v0 offset:1024
	ds_read_b128 v[240:243], v0 offset:2048
	ds_read_b128 v[244:247], v0 offset:3072
	global_load_lds_dwordx4 v[198:199], off
	v_lshl_add_u64 v[218:219], s[24:25], 0, v[174:175]
	s_add_i32 m0, s43, 0x2000
	s_nop 0
	global_load_lds_dwordx4 v[218:219], off
	s_barrier
	s_waitcnt lgkmcnt(0)
	s_setprio 1
	s_waitcnt lgkmcnt(0)
	v_mfma_f32_16x16x32_bf16 v[118:121], v[232:235], v[146:149], 0
	v_mfma_f32_16x16x32_bf16 v[114:117], v[240:243], v[146:149], 0
	v_mfma_f32_16x16x32_bf16 v[102:105], v[232:235], v[154:157], 0
	v_mfma_f32_16x16x32_bf16 v[98:101], v[240:243], v[154:157], 0
	v_mfma_f32_16x16x32_bf16 v[86:89], v[232:235], v[186:189], 0
	v_mfma_f32_16x16x32_bf16 v[82:85], v[240:243], v[186:189], 0
	v_mfma_f32_16x16x32_bf16 v[70:73], v[232:235], v[194:197], 0
	v_mfma_f32_16x16x32_bf16 v[66:69], v[240:243], v[194:197], 0
	v_mfma_f32_16x16x32_bf16 v[118:121], v[236:239], v[150:153], v[118:121]
	v_mfma_f32_16x16x32_bf16 v[114:117], v[244:247], v[150:153], v[114:117]
	v_mfma_f32_16x16x32_bf16 v[102:105], v[236:239], v[158:161], v[102:105]
	v_mfma_f32_16x16x32_bf16 v[98:101], v[244:247], v[158:161], v[98:101]
	v_mfma_f32_16x16x32_bf16 v[86:89], v[236:239], v[190:193], v[86:89]
	v_mfma_f32_16x16x32_bf16 v[82:85], v[244:247], v[190:193], v[82:85]
	v_mfma_f32_16x16x32_bf16 v[70:73], v[236:239], v[214:217], v[70:73]
	v_mfma_f32_16x16x32_bf16 v[66:69], v[244:247], v[214:217], v[66:69]
	s_setprio 0
	s_mov_b32 m0, s31
	v_lshl_add_u64 v[248:249], s[20:21], 0, v[168:169]
	s_barrier
	ds_read_b128 v[146:149], v212 offset:16384
	ds_read_b128 v[150:153], v212 offset:17408
	ds_read_b128 v[154:157], v212 offset:18432
	ds_read_b128 v[158:161], v212 offset:19456
	ds_read_b128 v[186:189], v212 offset:20480
	ds_read_b128 v[190:193], v212 offset:21504
	ds_read_b128 v[194:197], v212 offset:22528
	ds_read_b128 v[214:217], v212 offset:23552
	global_load_lds_dwordx4 v[248:249], off
	v_lshl_add_u64 v[250:251], s[20:21], 0, v[172:173]
	s_mov_b32 m0, s95
	s_nop 0
	global_load_lds_dwordx4 v[250:251], off
	s_barrier
	s_waitcnt lgkmcnt(0)
	s_setprio 1
	s_waitcnt lgkmcnt(0)
	v_mfma_f32_16x16x32_bf16 v[62:65], v[130:133], v[146:149], 0
	v_mfma_f32_16x16x32_bf16 v[58:61], v[138:141], v[146:149], 0
	v_mfma_f32_16x16x32_bf16 v[46:49], v[130:133], v[154:157], 0
	v_mfma_f32_16x16x32_bf16 v[42:45], v[138:141], v[154:157], 0
	v_mfma_f32_16x16x32_bf16 v[30:33], v[130:133], v[186:189], 0
	v_mfma_f32_16x16x32_bf16 v[26:29], v[138:141], v[186:189], 0
	v_mfma_f32_16x16x32_bf16 v[14:17], v[130:133], v[194:197], 0
	v_mfma_f32_16x16x32_bf16 v[10:13], v[138:141], v[194:197], 0
	v_mfma_f32_16x16x32_bf16 v[62:65], v[134:137], v[150:153], v[62:65]
	v_mfma_f32_16x16x32_bf16 v[58:61], v[142:145], v[150:153], v[58:61]
	v_mfma_f32_16x16x32_bf16 v[46:49], v[134:137], v[158:161], v[46:49]
	v_mfma_f32_16x16x32_bf16 v[42:45], v[142:145], v[158:161], v[42:45]
	v_mfma_f32_16x16x32_bf16 v[30:33], v[134:137], v[190:193], v[30:33]
	v_mfma_f32_16x16x32_bf16 v[26:29], v[142:145], v[190:193], v[26:29]
	v_mfma_f32_16x16x32_bf16 v[14:17], v[134:137], v[214:217], v[14:17]
	v_mfma_f32_16x16x32_bf16 v[10:13], v[142:145], v[214:217], v[10:13]
	s_setprio 0
	s_barrier
	s_add_u32 s24, s24, s60
	s_addc_u32 s25, s25, 0
	s_add_i32 s43, s44, s30
	v_lshl_add_u64 v[226:227], s[24:25], 0, v[170:171]
	s_mov_b32 m0, s43
	v_lshl_add_u64 v[228:229], s[24:25], 0, v[174:175]
	global_load_lds_dwordx4 v[226:227], off
	s_add_i32 m0, s43, 0x2000
	s_nop 0
	global_load_lds_dwordx4 v[228:229], off
	s_waitcnt vmcnt(6)
	s_barrier
	s_setprio 1
	v_mfma_f32_16x16x32_bf16 v[54:57], v[232:235], v[146:149], 0
	v_mfma_f32_16x16x32_bf16 v[50:53], v[240:243], v[146:149], 0
	v_mfma_f32_16x16x32_bf16 v[38:41], v[232:235], v[154:157], 0
	v_mfma_f32_16x16x32_bf16 v[34:37], v[240:243], v[154:157], 0
	v_mfma_f32_16x16x32_bf16 v[22:25], v[232:235], v[186:189], 0
	v_mfma_f32_16x16x32_bf16 v[18:21], v[240:243], v[186:189], 0
	v_mfma_f32_16x16x32_bf16 v[6:9], v[232:235], v[194:197], 0
	v_mfma_f32_16x16x32_bf16 v[2:5], v[240:243], v[194:197], 0
	v_mfma_f32_16x16x32_bf16 v[54:57], v[236:239], v[150:153], v[54:57]
	v_mfma_f32_16x16x32_bf16 v[50:53], v[244:247], v[150:153], v[50:53]
	v_mfma_f32_16x16x32_bf16 v[38:41], v[236:239], v[158:161], v[38:41]
	v_mfma_f32_16x16x32_bf16 v[34:37], v[244:247], v[158:161], v[34:37]
	v_mfma_f32_16x16x32_bf16 v[22:25], v[236:239], v[190:193], v[22:25]
	v_mfma_f32_16x16x32_bf16 v[18:21], v[244:247], v[190:193], v[18:21]
	v_mfma_f32_16x16x32_bf16 v[6:9], v[236:239], v[214:217], v[6:9]
	v_mfma_f32_16x16x32_bf16 v[2:5], v[244:247], v[214:217], v[2:5]
	s_setprio 0
	s_add_i32 s24, 0, 0x18000
	v_add_u32_e32 v0, s24, v211
	s_barrier
	ds_read_b128 v[130:133], v0
	ds_read_b128 v[134:137], v0 offset:1024
	ds_read_b128 v[138:141], v0 offset:2048
	ds_read_b128 v[142:145], v0 offset:3072
	s_add_u32 s20, s20, s60
	s_addc_u32 s21, s21, 0
	s_mov_b32 m0, s8
	v_lshl_add_u64 v[232:233], s[20:21], 0, v[168:169]
	ds_read_b128 v[146:149], v212 offset:32768
	ds_read_b128 v[150:153], v212 offset:33792
	ds_read_b128 v[154:157], v212 offset:34816
	ds_read_b128 v[158:161], v212 offset:35840
	ds_read_b128 v[186:189], v212 offset:36864
	ds_read_b128 v[190:193], v212 offset:37888
	ds_read_b128 v[194:197], v212 offset:38912
	ds_read_b128 v[214:217], v212 offset:39936
	global_load_lds_dwordx4 v[232:233], off
	v_lshl_add_u64 v[232:233], s[20:21], 0, v[172:173]
	s_mov_b32 m0, s9
	s_nop 0
	global_load_lds_dwordx4 v[232:233], off
	s_waitcnt lgkmcnt(8)
	s_barrier
	s_waitcnt lgkmcnt(0)
	s_setprio 1
	s_waitcnt lgkmcnt(0)
	v_mfma_f32_16x16x32_bf16 v[126:129], v[130:133], v[146:149], v[126:129]
	v_mfma_f32_16x16x32_bf16 v[122:125], v[138:141], v[146:149], v[122:125]
	v_mfma_f32_16x16x32_bf16 v[110:113], v[130:133], v[154:157], v[110:113]
	v_mfma_f32_16x16x32_bf16 v[106:109], v[138:141], v[154:157], v[106:109]
	v_mfma_f32_16x16x32_bf16 v[94:97], v[130:133], v[186:189], v[94:97]
	v_mfma_f32_16x16x32_bf16 v[90:93], v[138:141], v[186:189], v[90:93]
	v_mfma_f32_16x16x32_bf16 v[78:81], v[130:133], v[194:197], v[78:81]
	v_mfma_f32_16x16x32_bf16 v[74:77], v[138:141], v[194:197], v[74:77]
	v_mfma_f32_16x16x32_bf16 v[126:129], v[134:137], v[150:153], v[126:129]
	v_mfma_f32_16x16x32_bf16 v[122:125], v[142:145], v[150:153], v[122:125]
	v_mfma_f32_16x16x32_bf16 v[110:113], v[134:137], v[158:161], v[110:113]
	v_mfma_f32_16x16x32_bf16 v[106:109], v[142:145], v[158:161], v[106:109]
	v_mfma_f32_16x16x32_bf16 v[94:97], v[134:137], v[190:193], v[94:97]
	v_mfma_f32_16x16x32_bf16 v[90:93], v[142:145], v[190:193], v[90:93]
	v_mfma_f32_16x16x32_bf16 v[78:81], v[134:137], v[214:217], v[78:81]
	v_mfma_f32_16x16x32_bf16 v[74:77], v[142:145], v[214:217], v[74:77]
	s_setprio 0
	s_barrier
	s_add_i32 s20, 0, 0x1c000
	s_add_i32 s21, s24, s30
	v_add_u32_e32 v0, s20, v211
	v_lshl_add_u64 v[198:199], v[198:199], 0, s[16:17]
	s_mov_b32 m0, s21
	ds_read_b128 v[232:235], v0
	ds_read_b128 v[236:239], v0 offset:1024
	ds_read_b128 v[240:243], v0 offset:2048
	ds_read_b128 v[244:247], v0 offset:3072
	global_load_lds_dwordx4 v[198:199], off
	v_lshl_add_u64 v[198:199], v[218:219], 0, s[16:17]
	s_add_i32 m0, s21, 0x2000
	s_nop 0
	global_load_lds_dwordx4 v[198:199], off
	s_barrier
	s_waitcnt lgkmcnt(0)
	s_setprio 1
	s_waitcnt lgkmcnt(0)
	v_mfma_f32_16x16x32_bf16 v[118:121], v[232:235], v[146:149], v[118:121]
	v_mfma_f32_16x16x32_bf16 v[114:117], v[240:243], v[146:149], v[114:117]
	v_mfma_f32_16x16x32_bf16 v[102:105], v[232:235], v[154:157], v[102:105]
	v_mfma_f32_16x16x32_bf16 v[98:101], v[240:243], v[154:157], v[98:101]
	v_mfma_f32_16x16x32_bf16 v[86:89], v[232:235], v[186:189], v[86:89]
	v_mfma_f32_16x16x32_bf16 v[82:85], v[240:243], v[186:189], v[82:85]
	v_mfma_f32_16x16x32_bf16 v[70:73], v[232:235], v[194:197], v[70:73]
	v_mfma_f32_16x16x32_bf16 v[66:69], v[240:243], v[194:197], v[66:69]
	v_mfma_f32_16x16x32_bf16 v[118:121], v[236:239], v[150:153], v[118:121]
	v_mfma_f32_16x16x32_bf16 v[114:117], v[244:247], v[150:153], v[114:117]
	v_mfma_f32_16x16x32_bf16 v[102:105], v[236:239], v[158:161], v[102:105]
	v_mfma_f32_16x16x32_bf16 v[98:101], v[244:247], v[158:161], v[98:101]
	v_mfma_f32_16x16x32_bf16 v[86:89], v[236:239], v[190:193], v[86:89]
	v_mfma_f32_16x16x32_bf16 v[82:85], v[244:247], v[190:193], v[82:85]
	v_mfma_f32_16x16x32_bf16 v[70:73], v[236:239], v[214:217], v[70:73]
	v_mfma_f32_16x16x32_bf16 v[66:69], v[244:247], v[214:217], v[66:69]
	s_setprio 0
	s_mov_b32 m0, s97
	v_lshl_add_u64 v[198:199], v[248:249], 0, s[16:17]
	s_barrier
	ds_read_b128 v[146:149], v212 offset:49152
	ds_read_b128 v[150:153], v212 offset:50176
	ds_read_b128 v[154:157], v212 offset:51200
	ds_read_b128 v[158:161], v212 offset:52224
	ds_read_b128 v[186:189], v212 offset:53248
	ds_read_b128 v[190:193], v212 offset:54272
	ds_read_b128 v[194:197], v212 offset:55296
	ds_read_b128 v[214:217], v212 offset:56320
	global_load_lds_dwordx4 v[198:199], off
	v_lshl_add_u64 v[198:199], v[250:251], 0, s[16:17]
	s_mov_b32 m0, s90
	s_nop 0
	global_load_lds_dwordx4 v[198:199], off
	s_barrier
	s_waitcnt lgkmcnt(0)
	s_setprio 1
	s_waitcnt lgkmcnt(0)
	v_mfma_f32_16x16x32_bf16 v[62:65], v[130:133], v[146:149], v[62:65]
	v_mfma_f32_16x16x32_bf16 v[58:61], v[138:141], v[146:149], v[58:61]
	v_mfma_f32_16x16x32_bf16 v[46:49], v[130:133], v[154:157], v[46:49]
	v_mfma_f32_16x16x32_bf16 v[42:45], v[138:141], v[154:157], v[42:45]
	v_mfma_f32_16x16x32_bf16 v[30:33], v[130:133], v[186:189], v[30:33]
	v_mfma_f32_16x16x32_bf16 v[26:29], v[138:141], v[186:189], v[26:29]
	v_mfma_f32_16x16x32_bf16 v[14:17], v[130:133], v[194:197], v[14:17]
	v_mfma_f32_16x16x32_bf16 v[10:13], v[138:141], v[194:197], v[10:13]
	v_mfma_f32_16x16x32_bf16 v[62:65], v[134:137], v[150:153], v[62:65]
	v_mfma_f32_16x16x32_bf16 v[58:61], v[142:145], v[150:153], v[58:61]
	v_mfma_f32_16x16x32_bf16 v[46:49], v[134:137], v[158:161], v[46:49]
	v_mfma_f32_16x16x32_bf16 v[42:45], v[142:145], v[158:161], v[42:45]
	v_mfma_f32_16x16x32_bf16 v[30:33], v[134:137], v[190:193], v[30:33]
	v_mfma_f32_16x16x32_bf16 v[26:29], v[142:145], v[190:193], v[26:29]
	v_mfma_f32_16x16x32_bf16 v[14:17], v[134:137], v[214:217], v[14:17]
	v_mfma_f32_16x16x32_bf16 v[10:13], v[142:145], v[214:217], v[10:13]
	s_setprio 0
	s_barrier
	s_add_i32 s20, s20, s30
	v_lshl_add_u64 v[130:131], v[226:227], 0, s[16:17]
	s_mov_b32 m0, s20
	s_nop 0
	global_load_lds_dwordx4 v[130:131], off
	v_lshl_add_u64 v[130:131], v[228:229], 0, s[16:17]
	s_add_i32 m0, s20, 0x2000
	s_nop 0
	global_load_lds_dwordx4 v[130:131], off
	s_waitcnt vmcnt(6)
	s_barrier
	s_setprio 1
	v_mfma_f32_16x16x32_bf16 v[54:57], v[232:235], v[146:149], v[54:57]
	v_mfma_f32_16x16x32_bf16 v[50:53], v[240:243], v[146:149], v[50:53]
	v_mfma_f32_16x16x32_bf16 v[38:41], v[232:235], v[154:157], v[38:41]
	v_mfma_f32_16x16x32_bf16 v[34:37], v[240:243], v[154:157], v[34:37]
	v_mfma_f32_16x16x32_bf16 v[22:25], v[232:235], v[186:189], v[22:25]
	v_mfma_f32_16x16x32_bf16 v[18:21], v[240:243], v[186:189], v[18:21]
	v_mfma_f32_16x16x32_bf16 v[6:9], v[232:235], v[194:197], v[6:9]
	v_mfma_f32_16x16x32_bf16 v[2:5], v[240:243], v[194:197], v[2:5]
	v_mfma_f32_16x16x32_bf16 v[54:57], v[236:239], v[150:153], v[54:57]
	v_mfma_f32_16x16x32_bf16 v[50:53], v[244:247], v[150:153], v[50:53]
	v_mfma_f32_16x16x32_bf16 v[38:41], v[236:239], v[158:161], v[38:41]
	v_mfma_f32_16x16x32_bf16 v[34:37], v[244:247], v[158:161], v[34:37]
	v_mfma_f32_16x16x32_bf16 v[22:25], v[236:239], v[190:193], v[22:25]
	v_mfma_f32_16x16x32_bf16 v[18:21], v[244:247], v[190:193], v[18:21]
	v_mfma_f32_16x16x32_bf16 v[6:9], v[236:239], v[214:217], v[6:9]
	v_mfma_f32_16x16x32_bf16 v[2:5], v[244:247], v[214:217], v[2:5]
	s_setprio 0
	s_add_u32 s38, s38, 0x100
	s_addc_u32 s39, s39, 0
	s_add_u32 s18, s18, 0x100
	s_addc_u32 s19, s19, 0
	s_cmp_ge_u32 s42, s91
	s_mov_b32 s20, s42
	s_barrier
	s_cbranch_scc0 .LBB0_919
	s_branch .Lgemm_k_done

.Lgemm_k_done:
	s_lshl_b32 s6, s6, 8
	s_and_b32 s6, s6, 0x7f00
	v_add_u32_e32 v186, s6, v210
	s_mov_b64 s[18:19], -1
	s_mov_b64 s[20:21], 0
	s_cmp_lt_i32 s96, 5
	s_mov_b64 s[38:39], 0
	s_cbranch_scc1 .LBB0_1060
	s_cmp_gt_i32 s96, 6
	s_cbranch_scc0 .LBB0_1056
	s_cmp_gt_i32 s96, 7
	s_cbranch_scc0 .LBB0_990
	s_cmp_eq_u32 s96, 8
	s_mov_b64 s[38:39], -1
	s_cbranch_scc0 .LBB0_989
	s_lshl_b32 s18, s5, 8
	s_ashr_i32 s19, s18, 31
	v_ashrrev_i32_e32 v187, 31, v186
	v_mov_b32_e32 v189, s19
	v_or_b32_e32 v188, s18, v162
	v_lshlrev_b64 v[192:193], 10, v[186:187]
	v_lshl_add_u64 v[130:131], v[192:193], 0, v[188:189]
	v_lshlrev_b64 v[130:131], 1, v[130:131]
	v_lshl_add_u64 v[132:133], s[0:1], 0, v[130:131]
	global_load_dwordx4 v[154:157], v[132:133], off
	v_lshl_add_u64 v[132:133], s[54:55], 0, v[130:131]
	v_or_b32_e32 v130, 0x100, v130
	v_lshl_add_u64 v[130:131], s[0:1], 0, v[130:131]
	global_load_dwordx4 v[158:161], v[132:133], off
	global_load_dwordx4 v[146:149], v[130:131], off
	global_load_dwordx4 v[150:153], v[132:133], off offset:256
	v_or_b32_e32 v130, 16, v186
	v_ashrrev_i32_e32 v131, 31, v130
	v_lshlrev_b64 v[190:191], 10, v[130:131]
	v_lshl_add_u64 v[130:131], v[190:191], 0, v[188:189]
	v_lshlrev_b64 v[130:131], 1, v[130:131]
	v_lshl_add_u64 v[132:133], s[0:1], 0, v[130:131]
	v_lshl_add_u64 v[134:135], s[54:55], 0, v[130:131]
	v_or_b32_e32 v130, 0x100, v130
	v_lshl_add_u64 v[130:131], s[0:1], 0, v[130:131]
	global_load_dwordx4 v[138:141], v[132:133], off
	global_load_dwordx4 v[142:145], v[134:135], off
	s_nop 0
	global_load_dwordx4 v[130:133], v[130:131], off
	s_nop 0
	global_load_dwordx4 v[134:137], v[134:135], off offset:256
	v_lshl_add_u64 v[194:195], v[192:193], 0, s[18:19]
	v_or_b32_e32 v194, v194, v162
	v_cndmask_b32_e64 v0, 0, 1, s[68:69]
	v_cmp_ne_u32_e64 s[42:43], 1, v0
	s_andn2_b64 vcc, exec, s[68:69]
	s_waitcnt vmcnt(0)
	v_lshlrev_b32_e32 v214, 16, v154
	v_and_b32_e32 v215, 0xffff0000, v154
	v_lshlrev_b32_e32 v154, 16, v155
	v_and_b32_e32 v155, 0xffff0000, v155
	v_lshlrev_b32_e32 v192, 16, v158
	v_and_b32_e32 v193, 0xffff0000, v158
	v_lshlrev_b32_e32 v158, 16, v159
	v_and_b32_e32 v159, 0xffff0000, v159
	v_lshlrev_b32_e32 v196, 16, v160
	v_and_b32_e32 v197, 0xffff0000, v160
	v_lshlrev_b32_e32 v198, 16, v161
	v_and_b32_e32 v199, 0xffff0000, v161
	v_lshlrev_b32_e32 v216, 16, v156
	v_and_b32_e32 v217, 0xffff0000, v156
	v_lshlrev_b32_e32 v156, 16, v157
	v_and_b32_e32 v157, 0xffff0000, v157
	v_pk_fma_f32 v[160:161], v[128:129], v[158:159], v[154:155]
	v_pk_fma_f32 v[158:159], v[126:127], v[192:193], v[214:215]
	v_pk_fma_f32 v[156:157], v[124:125], v[198:199], v[156:157]
	v_pk_fma_f32 v[154:155], v[122:123], v[196:197], v[216:217]
	v_lshl_add_u64 v[192:193], v[194:195], 2, s[12:13]
	v_lshl_add_u64 v[194:195], v[194:195], 1, s[48:49]
	global_store_dwordx4 v[192:193], v[158:161], off
	global_store_dwordx4 v[192:193], v[154:157], off offset:16
	s_cbranch_vccnz .LBB0_926
	v_cvt_pk_bf16_f32 v196, v158, v159
	v_cvt_pk_bf16_f32 v197, v160, v161
	v_cvt_pk_bf16_f32 v198, v154, v155
	v_cvt_pk_bf16_f32 v199, v156, v157
	global_store_dwordx4 v[194:195], v[196:199], off
